# attention: row-sum ones fragment kept in dedicated registers (no per-tile v_mov)
# speedup vs baseline: 1.0261x; 1.0035x over previous
.LBB0_173:
	s_or_b64 exec, exec, s[6:7]
	s_add_i32 s6, s34, 1
	s_waitcnt vmcnt(1)
	v_add_u32_e32 v24, 0, v116
	s_add_u32 s34, s21, s35
	v_mov_b32_e32 v26, v157
	v_mov_b32_e32 v27, v157
	s_waitcnt vmcnt(0)
	ds_write_b128 v24, v[28:31] offset:13312
	s_addc_u32 s35, s10, 0
	v_mov_b32_e32 v24, v157
	v_mov_b32_e32 v25, v157
	v_mov_b64_e32 v[30:31], v[26:27]
	v_mov_b64_e32 v[34:35], v[26:27]
	v_mov_b64_e32 v[38:39], v[26:27]
	v_mov_b64_e32 v[42:43], v[26:27]
	v_mov_b64_e32 v[46:47], v[26:27]
	v_mov_b64_e32 v[50:51], v[26:27]
	v_mov_b64_e32 v[54:55], v[26:27]
	v_mov_b64_e32 v[58:59], v[26:27]
	v_mov_b64_e32 v[62:63], v[26:27]
	v_lshl_add_u64 v[132:133], v[120:121], 0, s[34:35]
	v_lshl_add_u64 v[134:135], v[122:123], 0, s[2:3]
	v_lshl_add_u64 v[136:137], v[124:125], 0, s[2:3]
	s_mov_b32 s7, 0
	v_mov_b32_e32 v128, 0xf149f2ca
	v_mov_b64_e32 v[28:29], v[24:25]
	v_mov_b64_e32 v[32:33], v[24:25]
	v_mov_b64_e32 v[36:37], v[24:25]
	v_mov_b64_e32 v[40:41], v[24:25]
	v_mov_b64_e32 v[44:45], v[24:25]
	v_mov_b64_e32 v[48:49], v[24:25]
	v_mov_b64_e32 v[52:53], v[24:25]
	v_mov_b64_e32 v[56:57], v[24:25]
	v_mov_b64_e32 v[60:61], v[24:25]
	v_mov_b32_e32 v130, 0xf149f2ca
	s_waitcnt lgkmcnt(0)
	s_barrier
	v_mov_b32_e32 v250, s52
	v_mov_b32_e32 v251, s52
	v_mov_b32_e32 v252, s52
	v_mov_b32_e32 v253, s52
	v_readfirstlane_b32 s2, v160
	s_cmpk_ge_u32 s2, 0x100
	s_cbranch_scc0 .Lattn_noprio
	s_setprio 1

.Lattn_sm:
	v_exp_f32_e32 v92, v92
	v_exp_f32_e32 v93, v93
	v_exp_f32_e32 v94, v94
	v_exp_f32_e32 v95, v95
	v_exp_f32_e32 v96, v96
	v_exp_f32_e32 v97, v97
	v_exp_f32_e32 v98, v98
	v_exp_f32_e32 v99, v99
	v_exp_f32_e32 v100, v100
	v_exp_f32_e32 v101, v101
	v_exp_f32_e32 v102, v102
	v_exp_f32_e32 v103, v103
	v_exp_f32_e32 v104, v104
	v_exp_f32_e32 v105, v105
	v_exp_f32_e32 v106, v106
	v_exp_f32_e32 v107, v107
	v_cvt_pk_bf16_f32 v92, v92, v93
	v_cvt_pk_bf16_f32 v93, v94, v95
	v_cvt_pk_bf16_f32 v94, v96, v97
	v_cvt_pk_bf16_f32 v95, v98, v99
	v_cvt_pk_bf16_f32 v96, v100, v101
	v_cvt_pk_bf16_f32 v97, v102, v103
	v_cvt_pk_bf16_f32 v98, v104, v105
	v_cvt_pk_bf16_f32 v99, v106, v107
	v_exp_f32_e32 v76, v76
	v_exp_f32_e32 v77, v77
	v_exp_f32_e32 v78, v78
	v_exp_f32_e32 v79, v79
	v_exp_f32_e32 v80, v80
	v_exp_f32_e32 v81, v81
	v_exp_f32_e32 v82, v82
	v_exp_f32_e32 v83, v83
	v_exp_f32_e32 v84, v84
	v_exp_f32_e32 v85, v85
	v_exp_f32_e32 v86, v86
	v_exp_f32_e32 v87, v87
	v_exp_f32_e32 v88, v88
	v_exp_f32_e32 v89, v89
	v_exp_f32_e32 v90, v90
	v_exp_f32_e32 v91, v91
	v_cvt_pk_bf16_f32 v76, v76, v77
	v_cvt_pk_bf16_f32 v77, v78, v79
	v_cvt_pk_bf16_f32 v78, v80, v81
	v_cvt_pk_bf16_f32 v79, v82, v83
	v_cvt_pk_bf16_f32 v80, v84, v85
	v_cvt_pk_bf16_f32 v81, v86, v87
	v_cvt_pk_bf16_f32 v82, v88, v89
	v_cvt_pk_bf16_f32 v83, v90, v91
	s_add_i32 s7, s7, 1
	s_bitcmp1_b32 s7, 0
	s_cselect_b32 s2, 0x5800, 0
	s_add_i32 s10, s2, 0
	v_add_u32_e32 v127, s10, v139
	v_add_u32_e32 v129, s10, v140
	v_add_u32_e32 v131, s10, v116
	s_waitcnt vmcnt(2)
	ds_write_b128 v127, v[72:75]
	s_waitcnt vmcnt(0)
	ds_write_b128 v131, v[64:67] offset:13312
	s_and_b64 vcc, exec, s[42:43]
	s_cbranch_vccz .Lattn_skipw
	ds_write_b128 v129, v[68:71]
.Lattn_skipw:
	s_waitcnt lgkmcnt(15)
	v_mfma_f32_16x16x32_bf16 v[60:63], v[234:237], v[92:95], v[60:63]
	v_mfma_f32_16x16x32_bf16 v[56:59], v[234:237], v[76:79], v[56:59]
	s_waitcnt lgkmcnt(14)
	v_mfma_f32_16x16x32_bf16 v[60:63], v[238:241], v[96:99], v[60:63]
	v_mfma_f32_16x16x32_bf16 v[56:59], v[238:241], v[80:83], v[56:59]
	s_waitcnt lgkmcnt(12)
	v_mfma_f32_16x16x32_bf16 v[52:55], v[242:245], v[92:95], v[52:55]
	v_mfma_f32_16x16x32_bf16 v[48:51], v[242:245], v[76:79], v[48:51]
	s_waitcnt lgkmcnt(10)
	v_mfma_f32_16x16x32_bf16 v[52:55], v[246:249], v[96:99], v[52:55]
	v_mfma_f32_16x16x32_bf16 v[48:51], v[246:249], v[80:83], v[48:51]
	s_waitcnt lgkmcnt(8)
	v_mfma_f32_16x16x32_bf16 v[44:47], v[162:165], v[92:95], v[44:47]
	v_mfma_f32_16x16x32_bf16 v[40:43], v[162:165], v[76:79], v[40:43]
	s_waitcnt lgkmcnt(6)
	v_mfma_f32_16x16x32_bf16 v[44:47], v[166:169], v[96:99], v[44:47]
	v_mfma_f32_16x16x32_bf16 v[40:43], v[166:169], v[80:83], v[40:43]
	s_waitcnt lgkmcnt(4)
	v_mfma_f32_16x16x32_bf16 v[36:39], v[170:173], v[92:95], v[36:39]
	v_mfma_f32_16x16x32_bf16 v[32:35], v[170:173], v[76:79], v[32:35]
	s_waitcnt lgkmcnt(2)
	v_mfma_f32_16x16x32_bf16 v[36:39], v[174:177], v[96:99], v[36:39]
	v_mfma_f32_16x16x32_bf16 v[32:35], v[174:177], v[80:83], v[32:35]
	v_mfma_f32_16x16x32_bf16 v[28:31], v[250:253], v[92:95], v[28:31]
	v_mfma_f32_16x16x32_bf16 v[24:27], v[250:253], v[76:79], v[24:27]
	v_mfma_f32_16x16x32_bf16 v[28:31], v[250:253], v[96:99], v[28:31]
	v_mfma_f32_16x16x32_bf16 v[24:27], v[250:253], v[80:83], v[24:27]
	s_waitcnt lgkmcnt(0)
	s_barrier
	v_lshl_add_u64 v[132:133], v[132:133], 0, s[50:51]
	v_lshl_add_u64 v[134:135], v[134:135], 0, s[4:5]
	v_lshl_add_u64 v[136:137], v[136:137], 0, s[4:5]
	s_cmp_eq_u32 s6, s7
	s_cbranch_scc0 .LBB0_175
	s_branch .LBB0_161
